# SwiGLU phases 5/11: epilogue row-statistics loads issued before the K-loop (no exposed wait per unit); on top of phase-2 rewrite
# speedup vs baseline: 1.0023x; 1.0013x over previous
; template <class Epi>
; DI void gemm_phase(LAS unsigned char* lds, int wid, int K, int lda, int ldb, bool bperm, const Sched3& S, const Epi& E) {
;     ...
; #pragma unroll
;         for (int a = 0; a < 2; ++a)
; #pragma unroll
;             for (int b = 0; b < 2; ++b)
; #pragma unroll
;                 for (int m = 0; m < 4; ++m)
; #pragma unroll
;                     for (int n = 0; n < 2; ++n) acc[a][b][m][n] = (f32x4){0.f, 0.f, 0.f, 0.f};
;         cur = nxt; cA = nA; cB = nB; hA = nhA; ++ui;
.LBB0_704:
	v_lshl_add_u32 v218, s22, 8, v155
	v_lshlrev_b32_e32 v218, 2, v218
	global_load_dword v220, v218, s[10:11]
	global_load_dword v221, v218, s[10:11] offset:64
	global_load_dword v222, v218, s[10:11] offset:128
	global_load_dword v223, v218, s[10:11] offset:192
	global_load_dword v224, v218, s[10:11] offset:512
	global_load_dword v225, v218, s[10:11] offset:576
	global_load_dword v226, v218, s[10:11] offset:640
	global_load_dword v227, v218, s[10:11] offset:704
	s_add_u32 s28, s28, 0x80080
	s_addc_u32 s29, s29, 0
	s_add_u32 s15, s30, 0x100
	v_mov_b32_e32 v0, 0
	s_addc_u32 s17, s31, 0
	s_mov_b32 s57, -2
	v_mov_b32_e32 v1, v0
	v_mov_b32_e32 v2, v0
	v_mov_b32_e32 v3, v0
	v_mov_b32_e32 v4, v0
	v_mov_b32_e32 v5, v0
	v_mov_b32_e32 v6, v0
	v_mov_b32_e32 v7, v0
	v_mov_b32_e32 v12, v0
	v_mov_b32_e32 v13, v0
	v_mov_b32_e32 v14, v0
	v_mov_b32_e32 v15, v0
	v_mov_b32_e32 v20, v0
	v_mov_b32_e32 v21, v0
	v_mov_b32_e32 v22, v0
	v_mov_b32_e32 v23, v0
	v_mov_b32_e32 v28, v0
	v_mov_b32_e32 v29, v0
	v_mov_b32_e32 v30, v0
	v_mov_b32_e32 v31, v0
	v_mov_b32_e32 v36, v0
	v_mov_b32_e32 v37, v0
	v_mov_b32_e32 v38, v0
	v_mov_b32_e32 v39, v0
	v_mov_b32_e32 v44, v0
	v_mov_b32_e32 v45, v0
	v_mov_b32_e32 v46, v0
	v_mov_b32_e32 v47, v0
	v_mov_b32_e32 v52, v0
	v_mov_b32_e32 v53, v0
	v_mov_b32_e32 v54, v0
	v_mov_b32_e32 v55, v0
	v_mov_b32_e32 v8, v0
	v_mov_b32_e32 v9, v0
	v_mov_b32_e32 v10, v0
	v_mov_b32_e32 v11, v0
	v_mov_b32_e32 v16, v0
	v_mov_b32_e32 v17, v0
	v_mov_b32_e32 v18, v0
	v_mov_b32_e32 v19, v0
	v_mov_b32_e32 v24, v0
	v_mov_b32_e32 v25, v0
	v_mov_b32_e32 v26, v0
	v_mov_b32_e32 v27, v0
	v_mov_b32_e32 v32, v0
	v_mov_b32_e32 v33, v0
	v_mov_b32_e32 v34, v0
	v_mov_b32_e32 v35, v0
	v_mov_b32_e32 v40, v0
	v_mov_b32_e32 v41, v0
	v_mov_b32_e32 v42, v0
	v_mov_b32_e32 v43, v0
	v_mov_b32_e32 v48, v0
	v_mov_b32_e32 v49, v0
	v_mov_b32_e32 v50, v0
	v_mov_b32_e32 v51, v0
	v_mov_b32_e32 v56, v0
	v_mov_b32_e32 v57, v0
	v_mov_b32_e32 v58, v0
	v_mov_b32_e32 v59, v0
	v_mov_b32_e32 v60, v0
	v_mov_b32_e32 v61, v0
	v_mov_b32_e32 v62, v0
	v_mov_b32_e32 v63, v0
	v_mov_b32_e32 v64, v0
	v_mov_b32_e32 v65, v0
	v_mov_b32_e32 v66, v0
	v_mov_b32_e32 v67, v0
	v_mov_b32_e32 v68, v0
	v_mov_b32_e32 v69, v0
	v_mov_b32_e32 v70, v0
	v_mov_b32_e32 v71, v0
	v_mov_b32_e32 v76, v0
	v_mov_b32_e32 v77, v0
	v_mov_b32_e32 v78, v0
	v_mov_b32_e32 v79, v0
	v_mov_b32_e32 v84, v0
	v_mov_b32_e32 v85, v0
	v_mov_b32_e32 v86, v0
	v_mov_b32_e32 v87, v0
	v_mov_b32_e32 v92, v0
	v_mov_b32_e32 v93, v0
	v_mov_b32_e32 v94, v0
	v_mov_b32_e32 v95, v0
	v_mov_b32_e32 v100, v0
	v_mov_b32_e32 v101, v0
	v_mov_b32_e32 v102, v0
	v_mov_b32_e32 v103, v0
	v_mov_b32_e32 v108, v0
	v_mov_b32_e32 v109, v0
	v_mov_b32_e32 v110, v0
	v_mov_b32_e32 v111, v0
	v_mov_b32_e32 v112, v0
	v_mov_b32_e32 v113, v0
	v_mov_b32_e32 v114, v0
	v_mov_b32_e32 v115, v0
	v_mov_b32_e32 v72, v0
	v_mov_b32_e32 v73, v0
	v_mov_b32_e32 v74, v0
	v_mov_b32_e32 v75, v0
	v_mov_b32_e32 v80, v0
	v_mov_b32_e32 v81, v0
	v_mov_b32_e32 v82, v0
	v_mov_b32_e32 v83, v0
	v_mov_b32_e32 v88, v0
	v_mov_b32_e32 v89, v0
	v_mov_b32_e32 v90, v0
	v_mov_b32_e32 v91, v0
	v_mov_b32_e32 v96, v0
	v_mov_b32_e32 v97, v0
	v_mov_b32_e32 v98, v0
	v_mov_b32_e32 v99, v0
	v_mov_b32_e32 v104, v0
	v_mov_b32_e32 v105, v0
	v_mov_b32_e32 v106, v0
	v_mov_b32_e32 v107, v0
	v_mov_b32_e32 v116, v0
	v_mov_b32_e32 v117, v0
	v_mov_b32_e32 v118, v0
	v_mov_b32_e32 v119, v0
	v_mov_b32_e32 v120, v0
	v_mov_b32_e32 v121, v0
	v_mov_b32_e32 v122, v0
	v_mov_b32_e32 v123, v0
	v_mov_b32_e32 v124, v0
	v_mov_b32_e32 v125, v0
	v_mov_b32_e32 v126, v0
	v_mov_b32_e32 v127, v0
.LBB0_705:
	ds_read_b128 v[138:141], v160
	ds_read_b128 v[142:145], v160 offset:1024
	ds_read_b128 v[146:149], v160 offset:2048
	ds_read_b128 v[150:153], v160 offset:3072
	s_add_u32 s30, s28, 0xfff80080
	s_addc_u32 s31, s29, -1
	s_cmp_eq_u32 s57, 28
	s_cselect_b32 s37, s25, s31
	s_cselect_b32 s36, s24, s30
	s_cselect_b32 s31, s27, s17
	s_cselect_b32 s30, s26, s15
	v_lshl_add_u64 v[156:157], s[28:29], 0, v[132:133]
	s_add_i32 m0, s23, 0xc000
	ds_read_b128 v[164:167], v161
	ds_read_b128 v[168:171], v161 offset:1024
	ds_read_b128 v[172:175], v161 offset:2048
	ds_read_b128 v[176:179], v161 offset:3072
	ds_read_b128 v[180:183], v161 offset:4096
	ds_read_b128 v[184:187], v161 offset:5120
	ds_read_b128 v[188:191], v161 offset:6144
	ds_read_b128 v[192:195], v161 offset:7168
	global_load_lds_dwordx4 v[156:157], off
	v_lshl_add_u64 v[156:157], s[28:29], 0, v[134:135]
	s_add_i32 m0, s23, 0xe000
	s_nop 0
	global_load_lds_dwordx4 v[156:157], off
	s_waitcnt lgkmcnt(8)
	s_barrier
	s_waitcnt lgkmcnt(0)
	s_setprio 1
	s_waitcnt lgkmcnt(0)
	v_mfma_f32_16x16x32_bf16 v[124:127], v[138:141], v[164:167], v[124:127]
	v_mfma_f32_16x16x32_bf16 v[120:123], v[146:149], v[164:167], v[120:123]
	v_mfma_f32_16x16x32_bf16 v[116:119], v[138:141], v[172:175], v[116:119]
	v_mfma_f32_16x16x32_bf16 v[104:107], v[146:149], v[172:175], v[104:107]
	v_mfma_f32_16x16x32_bf16 v[96:99], v[138:141], v[180:183], v[96:99]
	v_mfma_f32_16x16x32_bf16 v[88:91], v[146:149], v[180:183], v[88:91]
	v_mfma_f32_16x16x32_bf16 v[80:83], v[138:141], v[188:191], v[80:83]
	v_mfma_f32_16x16x32_bf16 v[72:75], v[146:149], v[188:191], v[72:75]
	v_mfma_f32_16x16x32_bf16 v[124:127], v[142:145], v[168:171], v[124:127]
	v_mfma_f32_16x16x32_bf16 v[120:123], v[150:153], v[168:171], v[120:123]
	v_mfma_f32_16x16x32_bf16 v[116:119], v[142:145], v[176:179], v[116:119]
	v_mfma_f32_16x16x32_bf16 v[104:107], v[150:153], v[176:179], v[104:107]
	v_mfma_f32_16x16x32_bf16 v[96:99], v[142:145], v[184:187], v[96:99]
	v_mfma_f32_16x16x32_bf16 v[88:91], v[150:153], v[184:187], v[88:91]
	v_mfma_f32_16x16x32_bf16 v[80:83], v[142:145], v[192:195], v[80:83]
	v_mfma_f32_16x16x32_bf16 v[72:75], v[150:153], v[192:195], v[72:75]
	s_setprio 0
	s_barrier
; #define PG8_STAGE(bufoff, gbase, voff) do { _Pragma("unroll") for (int _i = 0; _i < 2; ++_i) \
;         __builtin_amdgcn_global_load_lds((const unsigned*)((const char*)(gbase) + (voff)[_i]), (LAS unsigned*)(lds + (bufoff) + ldsw + _i * 8192), 16, 0, 0); } while (0)
; #define PG8_LDA(dst, b, h) do { _Pragma("unroll") for (int m = 0; m < 4; ++m) _Pragma("unroll") for (int k = 0; k < 2; ++k) dst[m][k] = *(const LAS bf16x8*)(lds + PG8_SA(b, h) + aoff + m * 2048 + k * 1024); } while (0)
; #define PG8_LDB(dst, b, h) do { _Pragma("unroll") for (int n = 0; n < 2; ++n) _Pragma("unroll") for (int k = 0; k < 2; ++k) dst[n][k] = *(const LAS bf16x8*)(lds + PG8_SB(b, h) + boff + n * 2048 + k * 1024); } while (0)
; #define PG8_WAIT_V(n) asm volatile("s_waitcnt vmcnt(" #n ")" ::: "memory")
; #define PG8_WAIT_L(n) asm volatile("s_waitcnt lgkmcnt(" #n ")" ::: "memory")
; #define PG8_BAR __builtin_amdgcn_s_barrier()
; #define PG8_SCHED __builtin_amdgcn_sched_barrier(0)
; template <class Epi>
; DI void gemm_phase(LAS unsigned char* lds, int wid, int K, int lda, int ldb, bool bperm, const Sched3& S, const Epi& E) {
;     ...
;             PG8_LDB(B0, 0, 0); PG8_SCHED; PG8_LDA(At, 0, 0); PG8_STAGE(PG8_SA(1, 1), a1 + hA, voffA);
;             PG8_WAIT_L(8); PG8_BAR; PG8_WAIT_L(0); PG8_MMA(0, 0, At, B0); PG8_BAR; PG8_SCHED;
;             PG8_LDB(B1, 0, 1); PG8_STAGE(PG8_SB(0, 0), b2, voffB);
;             PG8_BAR; PG8_WAIT_L(0); PG8_MMA(0, 1, At, B1); PG8_BAR;
;             PG8_LDA(At, 0, 1); PG8_STAGE(PG8_SA(0, 0), a2, voffA);
;             PG8_BAR; PG8_WAIT_L(0); if (full) PG8_MMA(1, 0, At, B0); PG8_BAR; PG8_SCHED;
;             PG8_STAGE(PG8_SB(0, 1), b2 + hstepB, voffB);
;             PG8_WAIT_V(6); PG8_BAR; if (full) PG8_MMA(1, 1, At, B1); PG8_BAR;
;             PG8_LDB(B0, 1, 0); PG8_SCHED; PG8_LDA(At, 1, 0); PG8_STAGE(PG8_SA(0, 1), a2 + h2, voffA);
;             PG8_WAIT_L(8); PG8_BAR; PG8_WAIT_L(0); PG8_MMA(0, 0, At, B0); PG8_BAR; PG8_SCHED;
;             PG8_LDB(B1, 1, 1); PG8_STAGE(PG8_SB(1, 0), b3, voffB);
;             PG8_BAR; PG8_WAIT_L(0); PG8_MMA(0, 1, At, B1); PG8_BAR;
;             PG8_LDA(At, 1, 1); PG8_STAGE(PG8_SA(1, 0), a3, voffA);
;             PG8_BAR; PG8_WAIT_L(0); if (full) PG8_MMA(1, 0, At, B0); PG8_BAR; PG8_SCHED;
;             PG8_STAGE(PG8_SB(1, 1), b3 + hstepB, voffB);
;             PG8_WAIT_V(6); PG8_BAR; if (full) PG8_MMA(1, 1, At, B1); PG8_BAR;
	s_add_i32 s58, s53, s43
	v_lshl_add_u64 v[156:157], s[30:31], 0, v[130:131]
	s_mov_b32 m0, s58
	ds_read_b128 v[196:199], v162
	ds_read_b128 v[200:203], v162 offset:1024
	ds_read_b128 v[204:207], v162 offset:2048
	ds_read_b128 v[208:211], v162 offset:3072
	global_load_lds_dwordx4 v[156:157], off
	v_lshl_add_u64 v[212:213], s[30:31], 0, v[128:129]
	s_add_i32 m0, s58, 0x2000
	s_nop 0
	global_load_lds_dwordx4 v[212:213], off
	s_barrier
	s_waitcnt lgkmcnt(0)
	s_setprio 1
	s_waitcnt lgkmcnt(0)
	v_mfma_f32_16x16x32_bf16 v[112:115], v[196:199], v[164:167], v[112:115]
	v_mfma_f32_16x16x32_bf16 v[108:111], v[204:207], v[164:167], v[108:111]
	v_mfma_f32_16x16x32_bf16 v[100:103], v[196:199], v[172:175], v[100:103]
	v_mfma_f32_16x16x32_bf16 v[92:95], v[204:207], v[172:175], v[92:95]
	v_mfma_f32_16x16x32_bf16 v[84:87], v[196:199], v[180:183], v[84:87]
	v_mfma_f32_16x16x32_bf16 v[76:79], v[204:207], v[180:183], v[76:79]
	v_mfma_f32_16x16x32_bf16 v[68:71], v[196:199], v[188:191], v[68:71]
	v_mfma_f32_16x16x32_bf16 v[64:67], v[204:207], v[188:191], v[64:67]
	v_mfma_f32_16x16x32_bf16 v[112:115], v[200:203], v[168:171], v[112:115]
	v_mfma_f32_16x16x32_bf16 v[108:111], v[208:211], v[168:171], v[108:111]
	v_mfma_f32_16x16x32_bf16 v[100:103], v[200:203], v[176:179], v[100:103]
	v_mfma_f32_16x16x32_bf16 v[92:95], v[208:211], v[176:179], v[92:95]
	v_mfma_f32_16x16x32_bf16 v[84:87], v[200:203], v[184:187], v[84:87]
	v_mfma_f32_16x16x32_bf16 v[76:79], v[208:211], v[184:187], v[76:79]
	v_mfma_f32_16x16x32_bf16 v[68:71], v[200:203], v[192:195], v[68:71]
	v_mfma_f32_16x16x32_bf16 v[64:67], v[208:211], v[192:195], v[64:67]
	s_setprio 0
	s_mov_b32 m0, s23
	v_lshl_add_u64 v[214:215], s[36:37], 0, v[130:131]
	s_barrier
	ds_read_b128 v[164:167], v161 offset:16384
	ds_read_b128 v[168:171], v161 offset:17408
	ds_read_b128 v[172:175], v161 offset:18432
	ds_read_b128 v[176:179], v161 offset:19456
	ds_read_b128 v[180:183], v161 offset:20480
	ds_read_b128 v[184:187], v161 offset:21504
	ds_read_b128 v[188:191], v161 offset:22528
	ds_read_b128 v[192:195], v161 offset:23552
	global_load_lds_dwordx4 v[214:215], off
	v_lshl_add_u64 v[216:217], s[36:37], 0, v[128:129]
	s_mov_b32 m0, s46
	s_nop 0
	global_load_lds_dwordx4 v[216:217], off
	s_barrier
	s_waitcnt lgkmcnt(0)
	s_setprio 1
	s_waitcnt lgkmcnt(0)
	v_mfma_f32_16x16x32_bf16 v[60:63], v[138:141], v[164:167], v[60:63]
	v_mfma_f32_16x16x32_bf16 v[56:59], v[146:149], v[164:167], v[56:59]
	v_mfma_f32_16x16x32_bf16 v[48:51], v[138:141], v[172:175], v[48:51]
	v_mfma_f32_16x16x32_bf16 v[40:43], v[146:149], v[172:175], v[40:43]
	v_mfma_f32_16x16x32_bf16 v[32:35], v[138:141], v[180:183], v[32:35]
	v_mfma_f32_16x16x32_bf16 v[24:27], v[146:149], v[180:183], v[24:27]
	v_mfma_f32_16x16x32_bf16 v[16:19], v[138:141], v[188:191], v[16:19]
	v_mfma_f32_16x16x32_bf16 v[8:11], v[146:149], v[188:191], v[8:11]
	v_mfma_f32_16x16x32_bf16 v[60:63], v[142:145], v[168:171], v[60:63]
	v_mfma_f32_16x16x32_bf16 v[56:59], v[150:153], v[168:171], v[56:59]
	v_mfma_f32_16x16x32_bf16 v[48:51], v[142:145], v[176:179], v[48:51]
	v_mfma_f32_16x16x32_bf16 v[40:43], v[150:153], v[176:179], v[40:43]
	v_mfma_f32_16x16x32_bf16 v[32:35], v[142:145], v[184:187], v[32:35]
	v_mfma_f32_16x16x32_bf16 v[24:27], v[150:153], v[184:187], v[24:27]
	v_mfma_f32_16x16x32_bf16 v[16:19], v[142:145], v[192:195], v[16:19]
	v_mfma_f32_16x16x32_bf16 v[8:11], v[150:153], v[192:195], v[8:11]
	s_setprio 0
	s_barrier
	s_add_u32 s58, s30, 0x80000
	s_addc_u32 s59, s31, 0
	s_add_i32 s60, s54, s43
	v_lshl_add_u64 v[138:139], s[58:59], 0, v[130:131]
	s_mov_b32 m0, s60
	s_nop 0
	global_load_lds_dwordx4 v[138:139], off
	v_lshl_add_u64 v[138:139], s[58:59], 0, v[128:129]
	s_add_i32 m0, s60, 0x2000
	s_nop 0
	global_load_lds_dwordx4 v[138:139], off
	s_waitcnt vmcnt(6)
	s_barrier
	s_setprio 1
	v_mfma_f32_16x16x32_bf16 v[52:55], v[196:199], v[164:167], v[52:55]
	v_mfma_f32_16x16x32_bf16 v[44:47], v[204:207], v[164:167], v[44:47]
	v_mfma_f32_16x16x32_bf16 v[36:39], v[196:199], v[172:175], v[36:39]
	v_mfma_f32_16x16x32_bf16 v[28:31], v[204:207], v[172:175], v[28:31]
	v_mfma_f32_16x16x32_bf16 v[20:23], v[196:199], v[180:183], v[20:23]
	v_mfma_f32_16x16x32_bf16 v[12:15], v[204:207], v[180:183], v[12:15]
	v_mfma_f32_16x16x32_bf16 v[4:7], v[196:199], v[188:191], v[4:7]
	v_mfma_f32_16x16x32_bf16 v[0:3], v[204:207], v[188:191], v[0:3]
	v_mfma_f32_16x16x32_bf16 v[52:55], v[200:203], v[168:171], v[52:55]
	v_mfma_f32_16x16x32_bf16 v[44:47], v[208:211], v[168:171], v[44:47]
	v_mfma_f32_16x16x32_bf16 v[36:39], v[200:203], v[176:179], v[36:39]
	v_mfma_f32_16x16x32_bf16 v[28:31], v[208:211], v[176:179], v[28:31]
	v_mfma_f32_16x16x32_bf16 v[20:23], v[200:203], v[184:187], v[20:23]
	v_mfma_f32_16x16x32_bf16 v[12:15], v[208:211], v[184:187], v[12:15]
	v_mfma_f32_16x16x32_bf16 v[4:7], v[200:203], v[192:195], v[4:7]
	v_mfma_f32_16x16x32_bf16 v[0:3], v[208:211], v[192:195], v[0:3]
	s_setprio 0
	s_add_i32 s58, 0, 0x18000
	v_add_u32_e32 v150, s58, v158
	s_barrier
	ds_read_b128 v[138:141], v150
	ds_read_b128 v[142:145], v150 offset:1024
	ds_read_b128 v[146:149], v150 offset:2048
	ds_read_b128 v[150:153], v150 offset:3072
	s_add_u32 s36, s36, 0x80000
	s_addc_u32 s37, s37, 0
	s_mov_b32 m0, s47
	v_lshl_add_u64 v[196:197], s[36:37], 0, v[130:131]
	ds_read_b128 v[164:167], v161 offset:32768
	ds_read_b128 v[168:171], v161 offset:33792
	ds_read_b128 v[172:175], v161 offset:34816
	ds_read_b128 v[176:179], v161 offset:35840
	ds_read_b128 v[180:183], v161 offset:36864
	ds_read_b128 v[184:187], v161 offset:37888
	ds_read_b128 v[188:191], v161 offset:38912
	ds_read_b128 v[192:195], v161 offset:39936
	global_load_lds_dwordx4 v[196:197], off
	v_lshl_add_u64 v[196:197], s[36:37], 0, v[128:129]
	s_mov_b32 m0, s48
	s_nop 0
	global_load_lds_dwordx4 v[196:197], off
	s_waitcnt lgkmcnt(8)
	s_barrier
; #define PG8_STAGE(bufoff, gbase, voff) do { _Pragma("unroll") for (int _i = 0; _i < 2; ++_i) \
;         __builtin_amdgcn_global_load_lds((const unsigned*)((const char*)(gbase) + (voff)[_i]), (LAS unsigned*)(lds + (bufoff) + ldsw + _i * 8192), 16, 0, 0); } while (0)
; #define PG8_LDA(dst, b, h) do { _Pragma("unroll") for (int m = 0; m < 4; ++m) _Pragma("unroll") for (int k = 0; k < 2; ++k) dst[m][k] = *(const LAS bf16x8*)(lds + PG8_SA(b, h) + aoff + m * 2048 + k * 1024); } while (0)
; #define PG8_LDB(dst, b, h) do { _Pragma("unroll") for (int n = 0; n < 2; ++n) _Pragma("unroll") for (int k = 0; k < 2; ++k) dst[n][k] = *(const LAS bf16x8*)(lds + PG8_SB(b, h) + boff + n * 2048 + k * 1024); } while (0)
; #define PG8_WAIT_V(n) asm volatile("s_waitcnt vmcnt(" #n ")" ::: "memory")
; #define PG8_WAIT_L(n) asm volatile("s_waitcnt lgkmcnt(" #n ")" ::: "memory")
; #define PG8_BAR __builtin_amdgcn_s_barrier()
; #define PG8_SCHED __builtin_amdgcn_sched_barrier(0)
; template <class Epi>
; DI void gemm_phase(LAS unsigned char* lds, int wid, int K, int lda, int ldb, bool bperm, const Sched3& S, const Epi& E) {
;     ...
;             PG8_LDB(B0, 0, 0); PG8_SCHED; PG8_LDA(At, 0, 0); PG8_STAGE(PG8_SA(1, 1), a1 + hA, voffA);
;             PG8_WAIT_L(8); PG8_BAR; PG8_WAIT_L(0); PG8_MMA(0, 0, At, B0); PG8_BAR; PG8_SCHED;
;             PG8_LDB(B1, 0, 1); PG8_STAGE(PG8_SB(0, 0), b2, voffB);
;             PG8_BAR; PG8_WAIT_L(0); PG8_MMA(0, 1, At, B1); PG8_BAR;
;             PG8_LDA(At, 0, 1); PG8_STAGE(PG8_SA(0, 0), a2, voffA);
;             PG8_BAR; PG8_WAIT_L(0); if (full) PG8_MMA(1, 0, At, B0); PG8_BAR; PG8_SCHED;
;             PG8_STAGE(PG8_SB(0, 1), b2 + hstepB, voffB);
;             PG8_WAIT_V(6); PG8_BAR; if (full) PG8_MMA(1, 1, At, B1); PG8_BAR;
;             PG8_LDB(B0, 1, 0); PG8_SCHED; PG8_LDA(At, 1, 0); PG8_STAGE(PG8_SA(0, 1), a2 + h2, voffA);
;             PG8_WAIT_L(8); PG8_BAR; PG8_WAIT_L(0); PG8_MMA(0, 0, At, B0); PG8_BAR; PG8_SCHED;
;             PG8_LDB(B1, 1, 1); PG8_STAGE(PG8_SB(1, 0), b3, voffB);
;             PG8_BAR; PG8_WAIT_L(0); PG8_MMA(0, 1, At, B1); PG8_BAR;
;             PG8_LDA(At, 1, 1); PG8_STAGE(PG8_SA(1, 0), a3, voffA);
;             PG8_BAR; PG8_WAIT_L(0); if (full) PG8_MMA(1, 0, At, B0); PG8_BAR; PG8_SCHED;
;             PG8_STAGE(PG8_SB(1, 1), b3 + hstepB, voffB);
;             PG8_WAIT_V(6); PG8_BAR; if (full) PG8_MMA(1, 1, At, B1); PG8_BAR;
	s_waitcnt lgkmcnt(0)
	s_setprio 1
	s_waitcnt lgkmcnt(0)
	v_mfma_f32_16x16x32_bf16 v[124:127], v[138:141], v[164:167], v[124:127]
	v_mfma_f32_16x16x32_bf16 v[120:123], v[146:149], v[164:167], v[120:123]
	v_mfma_f32_16x16x32_bf16 v[116:119], v[138:141], v[172:175], v[116:119]
	v_mfma_f32_16x16x32_bf16 v[104:107], v[146:149], v[172:175], v[104:107]
	v_mfma_f32_16x16x32_bf16 v[96:99], v[138:141], v[180:183], v[96:99]
	v_mfma_f32_16x16x32_bf16 v[88:91], v[146:149], v[180:183], v[88:91]
	v_mfma_f32_16x16x32_bf16 v[80:83], v[138:141], v[188:191], v[80:83]
	v_mfma_f32_16x16x32_bf16 v[72:75], v[146:149], v[188:191], v[72:75]
	v_mfma_f32_16x16x32_bf16 v[124:127], v[142:145], v[168:171], v[124:127]
	v_mfma_f32_16x16x32_bf16 v[120:123], v[150:153], v[168:171], v[120:123]
	v_mfma_f32_16x16x32_bf16 v[116:119], v[142:145], v[176:179], v[116:119]
	v_mfma_f32_16x16x32_bf16 v[104:107], v[150:153], v[176:179], v[104:107]
	v_mfma_f32_16x16x32_bf16 v[96:99], v[142:145], v[184:187], v[96:99]
	v_mfma_f32_16x16x32_bf16 v[88:91], v[150:153], v[184:187], v[88:91]
	v_mfma_f32_16x16x32_bf16 v[80:83], v[142:145], v[192:195], v[80:83]
	v_mfma_f32_16x16x32_bf16 v[72:75], v[150:153], v[192:195], v[72:75]
	s_setprio 0
	s_barrier
	s_add_i32 s36, 0, 0x1c000
	s_add_i32 s37, s58, s43
	v_add_u32_e32 v154, s36, v158
	v_lshl_add_u64 v[156:157], v[156:157], 0, s[8:9]
	s_mov_b32 m0, s37
	ds_read_b128 v[196:199], v154
	ds_read_b128 v[200:203], v154 offset:1024
	ds_read_b128 v[204:207], v154 offset:2048
	ds_read_b128 v[208:211], v154 offset:3072
	global_load_lds_dwordx4 v[156:157], off
	v_lshl_add_u64 v[156:157], v[212:213], 0, s[8:9]
	s_add_i32 m0, s37, 0x2000
	s_nop 0
	global_load_lds_dwordx4 v[156:157], off
	s_barrier
	s_waitcnt lgkmcnt(0)
	s_setprio 1
	s_waitcnt lgkmcnt(0)
	v_mfma_f32_16x16x32_bf16 v[112:115], v[196:199], v[164:167], v[112:115]
	v_mfma_f32_16x16x32_bf16 v[108:111], v[204:207], v[164:167], v[108:111]
	v_mfma_f32_16x16x32_bf16 v[100:103], v[196:199], v[172:175], v[100:103]
	v_mfma_f32_16x16x32_bf16 v[92:95], v[204:207], v[172:175], v[92:95]
	v_mfma_f32_16x16x32_bf16 v[84:87], v[196:199], v[180:183], v[84:87]
	v_mfma_f32_16x16x32_bf16 v[76:79], v[204:207], v[180:183], v[76:79]
	v_mfma_f32_16x16x32_bf16 v[68:71], v[196:199], v[188:191], v[68:71]
	v_mfma_f32_16x16x32_bf16 v[64:67], v[204:207], v[188:191], v[64:67]
	v_mfma_f32_16x16x32_bf16 v[112:115], v[200:203], v[168:171], v[112:115]
	v_mfma_f32_16x16x32_bf16 v[108:111], v[208:211], v[168:171], v[108:111]
	v_mfma_f32_16x16x32_bf16 v[100:103], v[200:203], v[176:179], v[100:103]
	v_mfma_f32_16x16x32_bf16 v[92:95], v[208:211], v[176:179], v[92:95]
	v_mfma_f32_16x16x32_bf16 v[84:87], v[200:203], v[184:187], v[84:87]
	v_mfma_f32_16x16x32_bf16 v[76:79], v[208:211], v[184:187], v[76:79]
	v_mfma_f32_16x16x32_bf16 v[68:71], v[200:203], v[192:195], v[68:71]
	v_mfma_f32_16x16x32_bf16 v[64:67], v[208:211], v[192:195], v[64:67]
	s_setprio 0
	s_mov_b32 m0, s49
	v_lshl_add_u64 v[156:157], v[214:215], 0, s[8:9]
	s_barrier
	ds_read_b128 v[164:167], v161 offset:49152
	ds_read_b128 v[168:171], v161 offset:50176
	ds_read_b128 v[172:175], v161 offset:51200
	ds_read_b128 v[176:179], v161 offset:52224
	ds_read_b128 v[180:183], v161 offset:53248
	ds_read_b128 v[184:187], v161 offset:54272
	ds_read_b128 v[188:191], v161 offset:55296
	ds_read_b128 v[192:195], v161 offset:56320
	global_load_lds_dwordx4 v[156:157], off
	v_lshl_add_u64 v[156:157], v[216:217], 0, s[8:9]
	s_mov_b32 m0, s50
	s_nop 0
	global_load_lds_dwordx4 v[156:157], off
	s_barrier
	s_waitcnt lgkmcnt(0)
	s_setprio 1
	s_waitcnt lgkmcnt(0)
	v_mfma_f32_16x16x32_bf16 v[60:63], v[138:141], v[164:167], v[60:63]
	v_mfma_f32_16x16x32_bf16 v[56:59], v[146:149], v[164:167], v[56:59]
	v_mfma_f32_16x16x32_bf16 v[48:51], v[138:141], v[172:175], v[48:51]
	v_mfma_f32_16x16x32_bf16 v[40:43], v[146:149], v[172:175], v[40:43]
	v_mfma_f32_16x16x32_bf16 v[32:35], v[138:141], v[180:183], v[32:35]
	v_mfma_f32_16x16x32_bf16 v[24:27], v[146:149], v[180:183], v[24:27]
	v_mfma_f32_16x16x32_bf16 v[16:19], v[138:141], v[188:191], v[16:19]
	v_mfma_f32_16x16x32_bf16 v[8:11], v[146:149], v[188:191], v[8:11]
	v_mfma_f32_16x16x32_bf16 v[60:63], v[142:145], v[168:171], v[60:63]
	v_mfma_f32_16x16x32_bf16 v[56:59], v[150:153], v[168:171], v[56:59]
	v_mfma_f32_16x16x32_bf16 v[48:51], v[142:145], v[176:179], v[48:51]
	v_mfma_f32_16x16x32_bf16 v[40:43], v[150:153], v[176:179], v[40:43]
	v_mfma_f32_16x16x32_bf16 v[32:35], v[142:145], v[184:187], v[32:35]
	v_mfma_f32_16x16x32_bf16 v[24:27], v[150:153], v[184:187], v[24:27]
	v_mfma_f32_16x16x32_bf16 v[16:19], v[142:145], v[192:195], v[16:19]
	v_mfma_f32_16x16x32_bf16 v[8:11], v[150:153], v[192:195], v[8:11]
	s_setprio 0
	s_barrier
	s_add_u32 s30, s30, 0x80080
	s_addc_u32 s31, s31, 0
	s_add_i32 s36, s36, s43
	v_lshl_add_u64 v[138:139], s[30:31], 0, v[130:131]
	s_mov_b32 m0, s36
	s_nop 0
	global_load_lds_dwordx4 v[138:139], off
	v_lshl_add_u64 v[138:139], s[30:31], 0, v[128:129]
	s_add_i32 m0, s36, 0x2000
	s_nop 0
	global_load_lds_dwordx4 v[138:139], off
	s_waitcnt vmcnt(6)
	s_barrier
; DI u32x2 pk4(f32x4 v) { u32x2 r; r.x = pk2(v[0], v[1]); r.y = pk2(v[2], v[3]); return r; }
; DI float silu_f(float x) { return x * __builtin_amdgcn_rcpf(1.f + __builtin_amdgcn_exp2f(-1.4426950409f * x)); }
; #define ROWS8 _Pragma("unroll") for (int ai = 0; ai < 2; ++ai) _Pragma("unroll") for (int m = 0; m < 4; ++m) if (ai == 0 || !hf)
; #define LOAD_ROW_RS(rsv, ssqp, invn) float rsv[2][4]; ROWS8_ALL rsv[ai][m] = (ssqp)[row0 + ai * HALF + m * 16]; ROWS8_ALL rsv[ai][m] = rstd_of(rsv[ai][m], invn)
;     DI void operator()(const Acc& acc, const Unit& u, int wr, int wc, int fr, int fq) const {
;     ...
;             LOAD_ROW_RS(rsv, SSQ(PH == 5 ? 2 : 6), 1.f / 2048.f);
;             const int ac0 = u.pn * 128 + wc * 32 + 8 * fq;
;             ROWS8 { const int r = row0 + ai * HALF + m * 16; const float rs = rsv[ai][m];
;                 u32x4 w;
; #pragma unroll
;                 for (int bj = 0; bj < 2; ++bj) { const f32x4 g = acc[ai][bj][m][0] * rs, uu = acc[ai][bj][m][1] * rs;
;                     f32x4 a; a[0] = silu_f(g[0]) * uu[0]; a[1] = silu_f(g[1]) * uu[1]; a[2] = silu_f(g[2]) * uu[2]; a[3] = silu_f(g[3]) * uu[3];
;                     const u32x2 h = pk4(a); if (bj == 0) { w.x = h.x; w.y = h.y; } else { w.z = h.x; w.w = h.y; } }
;                 *(u32x4*)(WSB(OFF_ACT) + (size_t)r * DFF + ac0) = w;
	s_setprio 1
	v_mfma_f32_16x16x32_bf16 v[52:55], v[196:199], v[164:167], v[52:55]
	v_mfma_f32_16x16x32_bf16 v[44:47], v[204:207], v[164:167], v[44:47]
	v_mfma_f32_16x16x32_bf16 v[36:39], v[196:199], v[172:175], v[36:39]
	v_mfma_f32_16x16x32_bf16 v[28:31], v[204:207], v[172:175], v[28:31]
	v_mfma_f32_16x16x32_bf16 v[20:23], v[196:199], v[180:183], v[20:23]
	v_mfma_f32_16x16x32_bf16 v[12:15], v[204:207], v[180:183], v[12:15]
	v_mfma_f32_16x16x32_bf16 v[4:7], v[196:199], v[188:191], v[4:7]
	v_mfma_f32_16x16x32_bf16 v[0:3], v[204:207], v[188:191], v[0:3]
	v_mfma_f32_16x16x32_bf16 v[52:55], v[200:203], v[168:171], v[52:55]
	v_mfma_f32_16x16x32_bf16 v[44:47], v[208:211], v[168:171], v[44:47]
	v_mfma_f32_16x16x32_bf16 v[36:39], v[200:203], v[176:179], v[36:39]
	v_mfma_f32_16x16x32_bf16 v[28:31], v[208:211], v[176:179], v[28:31]
	v_mfma_f32_16x16x32_bf16 v[20:23], v[200:203], v[184:187], v[20:23]
	v_mfma_f32_16x16x32_bf16 v[12:15], v[208:211], v[184:187], v[12:15]
	v_mfma_f32_16x16x32_bf16 v[4:7], v[200:203], v[192:195], v[4:7]
	v_mfma_f32_16x16x32_bf16 v[0:3], v[208:211], v[192:195], v[0:3]
	s_setprio 0
	s_add_i32 s57, s57, 2
	s_add_u32 s28, s28, 0x100
	s_addc_u32 s29, s29, 0
	s_add_u32 s15, s15, 0x100
	s_addc_u32 s17, s17, 0
	s_cmp_gt_u32 s57, 29
	s_barrier
	s_cbranch_scc0 .LBB0_705
	v_lshl_add_u32 v142, s22, 8, v155
	v_or_b32_e32 v156, 16, v142
	v_ashrrev_i32_e32 v157, 31, v156
	v_or_b32_e32 v152, 32, v142
	v_or_b32_e32 v150, 48, v142
	v_lshl_add_u64 v[138:139], v[156:157], 2, s[10:11]
	v_ashrrev_i32_e32 v153, 31, v152
	v_ashrrev_i32_e32 v151, 31, v150
	v_ashrrev_i32_e32 v143, 31, v142
	v_lshl_add_u64 v[140:141], v[152:153], 2, s[10:11]
	v_lshl_add_u64 v[144:145], v[150:151], 2, s[10:11]
	v_lshl_add_u64 v[146:147], v[142:143], 2, s[10:11]
	v_add_u32_e32 v148, 0x80, v142
	v_add_u32_e32 v146, 0x90, v142
	v_add_u32_e32 v144, 0xa0, v142
	v_add_u32_e32 v138, 0xb0, v142
	v_ashrrev_i32_e32 v149, 31, v148
	v_ashrrev_i32_e32 v147, 31, v146
	v_ashrrev_i32_e32 v145, 31, v144
	v_ashrrev_i32_e32 v139, 31, v138
	v_lshl_add_u64 v[140:141], v[148:149], 2, s[10:11]
	v_lshl_add_u64 v[164:165], v[146:147], 2, s[10:11]
	v_lshl_add_u64 v[166:167], v[144:145], 2, s[10:11]
	v_lshl_add_u64 v[168:169], v[138:139], 2, s[10:11]
	v_lshl_add_u32 v164, s56, 7, v159
	v_mov_b64_e32 v[140:141], s[12:13]
	v_ashrrev_i32_e32 v165, 31, v164
	v_mad_i64_i32 v[166:167], s[24:25], v142, s55, v[140:141]
	v_lshlrev_b64 v[142:143], 1, v[164:165]
	v_lshl_add_u64 v[164:165], v[166:167], 0, v[142:143]
	s_and_b64 vcc, exec, s[2:3]
	s_mov_b32 s56, s14
	s_mov_b32 s22, s16
	s_mov_b64 s[30:31], s[18:19]
	s_mov_b64 s[28:29], s[20:21]
	v_mov_b32_e32 v151, v221
	v_mov_b32_e32 v153, v222
	v_mov_b32_e32 v154, v223
	v_mov_b32_e32 v157, v220
	v_mov_b32_e32 v139, v224
	v_mov_b32_e32 v145, v225
	v_mov_b32_e32 v147, v226
	v_mov_b32_e32 v149, v227
	v_fmamk_f32 v151, v151, 0x3a000000, v163
	v_rsq_f32_e32 v168, v151
	v_fmamk_f32 v153, v153, 0x3a000000, v163
	v_fmamk_f32 v157, v157, 0x3a000000, v163
	v_rsq_f32_e32 v166, v157
	v_rsq_f32_e32 v170, v153
	v_pk_mul_f32 v[118:119], v[118:119], v[168:169] op_sel_hi:[1,0]
	v_pk_mul_f32 v[116:117], v[116:117], v[168:169] op_sel_hi:[1,0]
	v_pk_mul_f32 v[126:127], v[126:127], v[166:167] op_sel_hi:[1,0]
	v_pk_mul_f32 v[124:125], v[124:125], v[166:167] op_sel_hi:[1,0]
	v_pk_mul_f32 v[114:115], v[114:115], v[166:167] op_sel_hi:[1,0]
	v_pk_mul_f32 v[112:113], v[112:113], v[166:167] op_sel_hi:[1,0]
	v_pk_mul_f32 v[122:123], v[122:123], v[166:167] op_sel_hi:[1,0]
	v_pk_mul_f32 v[120:121], v[120:121], v[166:167] op_sel_hi:[1,0]
	v_pk_mul_f32 v[110:111], v[110:111], v[166:167] op_sel_hi:[1,0]
	v_pk_mul_f32 v[108:109], v[108:109], v[166:167] op_sel_hi:[1,0]
	v_mul_f32_e32 v151, 0xbfb8aa3b, v124
	v_mul_f32_e32 v153, 0xbfb8aa3b, v125
	v_mul_f32_e32 v157, 0xbfb8aa3b, v126
	v_mul_f32_e32 v166, 0xbfb8aa3b, v127
	v_mul_f32_e32 v167, 0xbfb8aa3b, v112
	v_mul_f32_e32 v169, 0xbfb8aa3b, v113
	v_mul_f32_e32 v171, 0xbfb8aa3b, v114
	v_mul_f32_e32 v172, 0xbfb8aa3b, v115
	v_exp_f32_e32 v151, v151
	v_exp_f32_e32 v153, v153
	v_exp_f32_e32 v157, v157
	v_exp_f32_e32 v166, v166
	v_exp_f32_e32 v167, v167
	v_exp_f32_e32 v169, v169
	v_exp_f32_e32 v171, v171
	v_exp_f32_e32 v172, v172
	v_mul_f32_e32 v173, 0xbfb8aa3b, v116
	v_exp_f32_e32 v178, v173
	v_add_f32_e32 v151, 1.0, v151
	v_add_f32_e32 v153, 1.0, v153
	v_add_f32_e32 v157, 1.0, v157
	v_add_f32_e32 v173, 1.0, v166
	v_add_f32_e32 v174, 1.0, v167
	v_add_f32_e32 v169, 1.0, v169
	v_add_f32_e32 v171, 1.0, v171
	v_add_f32_e32 v177, 1.0, v172
	v_rcp_f32_e32 v166, v151
	v_rcp_f32_e32 v167, v153
	v_rcp_f32_e32 v172, v157
	v_rcp_f32_e32 v173, v173
	v_rcp_f32_e32 v174, v174
	v_rcp_f32_e32 v175, v169
	v_rcp_f32_e32 v176, v171
	v_rcp_f32_e32 v177, v177
	v_pk_mul_f32 v[124:125], v[124:125], v[166:167]
	v_pk_mul_f32 v[126:127], v[126:127], v[172:173]
	v_pk_mul_f32 v[112:113], v[112:113], v[174:175]
	v_pk_mul_f32 v[114:115], v[114:115], v[176:177]
	v_pk_mul_f32 v[120:121], v[120:121], v[124:125]
	v_pk_mul_f32 v[122:123], v[122:123], v[126:127]
	v_pk_mul_f32 v[112:113], v[108:109], v[112:113]
	v_pk_mul_f32 v[114:115], v[110:111], v[114:115]
	v_cvt_pk_bf16_f32 v108, v120, v121
	v_cvt_pk_bf16_f32 v109, v122, v123
	v_cvt_pk_bf16_f32 v110, v112, v113
	v_cvt_pk_bf16_f32 v111, v114, v115
	global_store_dwordx4 v[164:165], v[108:111], off
	v_pk_mul_f32 v[104:105], v[104:105], v[168:169] op_sel_hi:[1,0]
	v_pk_mul_f32 v[106:107], v[106:107], v[168:169] op_sel_hi:[1,0]
	v_mul_f32_e32 v108, 0xbfb8aa3b, v117
	v_exp_f32_e32 v109, v108
	v_mul_f32_e32 v110, 0xbfb8aa3b, v118
	v_mul_f32_e32 v111, 0xbfb8aa3b, v119
	v_exp_f32_e32 v110, v110
	v_exp_f32_e32 v111, v111
; DI u32x2 pk4(f32x4 v) { u32x2 r; r.x = pk2(v[0], v[1]); r.y = pk2(v[2], v[3]); return r; }
; DI float silu_f(float x) { return x * __builtin_amdgcn_rcpf(1.f + __builtin_amdgcn_exp2f(-1.4426950409f * x)); }
; #define ROWS8 _Pragma("unroll") for (int ai = 0; ai < 2; ++ai) _Pragma("unroll") for (int m = 0; m < 4; ++m) if (ai == 0 || !hf)
;     DI void operator()(const Acc& acc, const Unit& u, int wr, int wc, int fr, int fq) const {
;     ...
;             ROWS8 { const int r = row0 + ai * HALF + m * 16; const float rs = rsv[ai][m];
;                 u32x4 w;
; #pragma unroll
;                 for (int bj = 0; bj < 2; ++bj) { const f32x4 g = acc[ai][bj][m][0] * rs, uu = acc[ai][bj][m][1] * rs;
;                     f32x4 a; a[0] = silu_f(g[0]) * uu[0]; a[1] = silu_f(g[1]) * uu[1]; a[2] = silu_f(g[2]) * uu[2]; a[3] = silu_f(g[3]) * uu[3];
;                     const u32x2 h = pk4(a); if (bj == 0) { w.x = h.x; w.y = h.y; } else { w.z = h.x; w.w = h.y; } }
;                 *(u32x4*)(WSB(OFF_ACT) + (size_t)r * DFF + ac0) = w;
	v_add_f32_e32 v108, 1.0, v178
	v_add_f32_e32 v109, 1.0, v109
	v_rcp_f32_e32 v108, v108
	v_rcp_f32_e32 v109, v109
	v_add_f32_e32 v110, 1.0, v110
	v_add_f32_e32 v111, 1.0, v111
	v_rcp_f32_e32 v110, v110
	v_rcp_f32_e32 v111, v111
	v_pk_mul_f32 v[108:109], v[116:117], v[108:109]
	v_pk_mul_f32 v[100:101], v[100:101], v[168:169] op_sel_hi:[1,0]
	v_pk_mul_f32 v[104:105], v[104:105], v[108:109]
	v_pk_mul_f32 v[108:109], v[118:119], v[110:111]
	v_cvt_pk_bf16_f32 v104, v104, v105
	v_pk_mul_f32 v[106:107], v[106:107], v[108:109]
	v_pk_mul_f32 v[102:103], v[102:103], v[168:169] op_sel_hi:[1,0]
	v_cvt_pk_bf16_f32 v105, v106, v107
	v_mul_f32_e32 v106, 0xbfb8aa3b, v100
	v_mul_f32_e32 v107, 0xbfb8aa3b, v101
	v_exp_f32_e32 v106, v106
	v_exp_f32_e32 v107, v107
	v_mul_f32_e32 v108, 0xbfb8aa3b, v102
	v_mul_f32_e32 v109, 0xbfb8aa3b, v103
	v_exp_f32_e32 v108, v108
	v_exp_f32_e32 v109, v109
	v_add_f32_e32 v106, 1.0, v106
	v_add_f32_e32 v107, 1.0, v107
	v_rcp_f32_e32 v106, v106
	v_rcp_f32_e32 v107, v107
	v_add_f32_e32 v108, 1.0, v108
	v_add_f32_e32 v109, 1.0, v109
	v_rcp_f32_e32 v108, v108
	v_rcp_f32_e32 v109, v109
	v_pk_mul_f32 v[92:93], v[92:93], v[168:169] op_sel_hi:[1,0]
	v_pk_mul_f32 v[100:101], v[100:101], v[106:107]
	v_pk_mul_f32 v[94:95], v[94:95], v[168:169] op_sel_hi:[1,0]
	v_pk_mul_f32 v[92:93], v[92:93], v[100:101]
	v_pk_mul_f32 v[100:101], v[102:103], v[108:109]
	v_cvt_pk_bf16_f32 v106, v92, v93
	v_pk_mul_f32 v[94:95], v[94:95], v[100:101]
	v_mad_i64_i32 v[92:93], s[24:25], v156, s55, v[140:141]
	v_cvt_pk_bf16_f32 v107, v94, v95
	v_lshl_add_u64 v[92:93], v[92:93], 0, v[142:143]
	global_store_dwordx4 v[92:93], v[104:107], off
	v_pk_mul_f32 v[92:93], v[98:99], v[170:171] op_sel_hi:[1,0]
	v_pk_mul_f32 v[94:95], v[96:97], v[170:171] op_sel_hi:[1,0]
	v_mul_f32_e32 v98, 0xbfb8aa3b, v92
	v_mul_f32_e32 v96, 0xbfb8aa3b, v94
	v_mul_f32_e32 v97, 0xbfb8aa3b, v95
	v_mul_f32_e32 v99, 0xbfb8aa3b, v93
	v_exp_f32_e32 v96, v96
	v_exp_f32_e32 v97, v97
	v_exp_f32_e32 v98, v98
	v_exp_f32_e32 v99, v99
	v_add_f32_e32 v96, 1.0, v96
	v_add_f32_e32 v97, 1.0, v97
	v_add_f32_e32 v98, 1.0, v98
	v_add_f32_e32 v99, 1.0, v99
	v_rcp_f32_e32 v96, v96
	v_rcp_f32_e32 v97, v97
	v_rcp_f32_e32 v98, v98
	v_rcp_f32_e32 v99, v99
	v_pk_mul_f32 v[90:91], v[90:91], v[170:171] op_sel_hi:[1,0]
	v_pk_mul_f32 v[88:89], v[88:89], v[170:171] op_sel_hi:[1,0]
	v_pk_mul_f32 v[94:95], v[94:95], v[96:97]
	v_pk_mul_f32 v[92:93], v[92:93], v[98:99]
	v_pk_mul_f32 v[88:89], v[88:89], v[94:95]
	v_pk_mul_f32 v[90:91], v[90:91], v[92:93]
	v_pk_mul_f32 v[84:85], v[84:85], v[170:171] op_sel_hi:[1,0]
	v_cvt_pk_bf16_f32 v88, v88, v89
	v_cvt_pk_bf16_f32 v89, v90, v91
	v_pk_mul_f32 v[86:87], v[86:87], v[170:171] op_sel_hi:[1,0]
	v_mul_f32_e32 v90, 0xbfb8aa3b, v84
	v_mul_f32_e32 v91, 0xbfb8aa3b, v85
	v_exp_f32_e32 v90, v90
	v_exp_f32_e32 v91, v91
	v_mul_f32_e32 v92, 0xbfb8aa3b, v86
	v_mul_f32_e32 v93, 0xbfb8aa3b, v87
	v_exp_f32_e32 v92, v92
	v_exp_f32_e32 v93, v93
	v_add_f32_e32 v90, 1.0, v90
	v_add_f32_e32 v91, 1.0, v91
	v_rcp_f32_e32 v90, v90
	v_rcp_f32_e32 v91, v91
	v_add_f32_e32 v92, 1.0, v92
	v_add_f32_e32 v93, 1.0, v93
	v_rcp_f32_e32 v92, v92
	v_rcp_f32_e32 v93, v93
	v_fmamk_f32 v154, v154, 0x3a000000, v163
	v_rsq_f32_e32 v154, v154
	v_pk_mul_f32 v[76:77], v[76:77], v[170:171] op_sel_hi:[1,0]
	v_pk_mul_f32 v[84:85], v[84:85], v[90:91]
	v_pk_mul_f32 v[78:79], v[78:79], v[170:171] op_sel_hi:[1,0]
	v_pk_mul_f32 v[76:77], v[76:77], v[84:85]
	v_pk_mul_f32 v[84:85], v[86:87], v[92:93]
	v_cvt_pk_bf16_f32 v90, v76, v77
	v_pk_mul_f32 v[78:79], v[78:79], v[84:85]
	v_mad_i64_i32 v[76:77], s[24:25], v152, s55, v[140:141]
	v_cvt_pk_bf16_f32 v91, v78, v79
	v_lshl_add_u64 v[76:77], v[76:77], 0, v[142:143]
	global_store_dwordx4 v[76:77], v[88:91], off
	v_pk_mul_f32 v[76:77], v[82:83], v[154:155] op_sel_hi:[1,0]
	v_pk_mul_f32 v[78:79], v[80:81], v[154:155] op_sel_hi:[1,0]
	v_mul_f32_e32 v82, 0xbfb8aa3b, v76
	v_mul_f32_e32 v80, 0xbfb8aa3b, v78
	v_mul_f32_e32 v81, 0xbfb8aa3b, v79
	v_mul_f32_e32 v83, 0xbfb8aa3b, v77
	v_exp_f32_e32 v80, v80
	v_exp_f32_e32 v81, v81
	v_exp_f32_e32 v82, v82
	v_exp_f32_e32 v83, v83
	v_add_f32_e32 v80, 1.0, v80
	v_add_f32_e32 v81, 1.0, v81
	v_add_f32_e32 v82, 1.0, v82
	v_add_f32_e32 v83, 1.0, v83
	v_rcp_f32_e32 v80, v80
	v_rcp_f32_e32 v81, v81
	v_rcp_f32_e32 v82, v82
	v_rcp_f32_e32 v83, v83
	v_pk_mul_f32 v[74:75], v[74:75], v[154:155] op_sel_hi:[1,0]
	v_pk_mul_f32 v[72:73], v[72:73], v[154:155] op_sel_hi:[1,0]
	v_pk_mul_f32 v[78:79], v[78:79], v[80:81]
	v_pk_mul_f32 v[76:77], v[76:77], v[82:83]
	v_pk_mul_f32 v[72:73], v[72:73], v[78:79]
	v_pk_mul_f32 v[74:75], v[74:75], v[76:77]
	v_pk_mul_f32 v[68:69], v[68:69], v[154:155] op_sel_hi:[1,0]
	v_cvt_pk_bf16_f32 v72, v72, v73
	v_cvt_pk_bf16_f32 v73, v74, v75
	v_pk_mul_f32 v[70:71], v[70:71], v[154:155] op_sel_hi:[1,0]
	v_mul_f32_e32 v74, 0xbfb8aa3b, v68
	v_mul_f32_e32 v75, 0xbfb8aa3b, v69
	v_exp_f32_e32 v74, v74
	v_exp_f32_e32 v75, v75
	v_mul_f32_e32 v76, 0xbfb8aa3b, v70
	v_mul_f32_e32 v77, 0xbfb8aa3b, v71
	v_exp_f32_e32 v76, v76
	v_exp_f32_e32 v77, v77
	v_add_f32_e32 v74, 1.0, v74
	v_add_f32_e32 v75, 1.0, v75
	v_rcp_f32_e32 v74, v74
	v_rcp_f32_e32 v75, v75
	v_add_f32_e32 v76, 1.0, v76
	v_add_f32_e32 v77, 1.0, v77
	v_rcp_f32_e32 v76, v76
	v_rcp_f32_e32 v77, v77
	v_pk_mul_f32 v[64:65], v[64:65], v[154:155] op_sel_hi:[1,0]
	v_pk_mul_f32 v[68:69], v[68:69], v[74:75]
	v_pk_mul_f32 v[66:67], v[66:67], v[154:155] op_sel_hi:[1,0]
	v_pk_mul_f32 v[64:65], v[64:65], v[68:69]
	v_pk_mul_f32 v[68:69], v[70:71], v[76:77]
	v_cvt_pk_bf16_f32 v74, v64, v65
	v_pk_mul_f32 v[66:67], v[66:67], v[68:69]
	v_mad_i64_i32 v[64:65], s[24:25], v150, s55, v[140:141]
; DI u32x2 pk4(f32x4 v) { u32x2 r; r.x = pk2(v[0], v[1]); r.y = pk2(v[2], v[3]); return r; }
; DI float silu_f(float x) { return x * __builtin_amdgcn_rcpf(1.f + __builtin_amdgcn_exp2f(-1.4426950409f * x)); }
; #define ROWS8 _Pragma("unroll") for (int ai = 0; ai < 2; ++ai) _Pragma("unroll") for (int m = 0; m < 4; ++m) if (ai == 0 || !hf)
;     DI void operator()(const Acc& acc, const Unit& u, int wr, int wc, int fr, int fq) const {
;     ...
;             ROWS8 { const int r = row0 + ai * HALF + m * 16; const float rs = rsv[ai][m];
;                 u32x4 w;
; #pragma unroll
;                 for (int bj = 0; bj < 2; ++bj) { const f32x4 g = acc[ai][bj][m][0] * rs, uu = acc[ai][bj][m][1] * rs;
;                     f32x4 a; a[0] = silu_f(g[0]) * uu[0]; a[1] = silu_f(g[1]) * uu[1]; a[2] = silu_f(g[2]) * uu[2]; a[3] = silu_f(g[3]) * uu[3];
;                     const u32x2 h = pk4(a); if (bj == 0) { w.x = h.x; w.y = h.y; } else { w.z = h.x; w.w = h.y; } }
;                 *(u32x4*)(WSB(OFF_ACT) + (size_t)r * DFF + ac0) = w;
	v_cvt_pk_bf16_f32 v75, v66, v67
	v_fmamk_f32 v66, v139, 0x3a000000, v163
	v_rsq_f32_e32 v68, v66
	v_lshl_add_u64 v[64:65], v[64:65], 0, v[142:143]
	global_store_dwordx4 v[64:65], v[72:75], off
	v_fmamk_f32 v65, v147, 0x3a000000, v163
	v_rsq_f32_e32 v66, v65
	v_fmamk_f32 v65, v145, 0x3a000000, v163
	v_pk_mul_f32 v[60:61], v[60:61], v[68:69] op_sel_hi:[1,0]
	v_rsq_f32_e32 v70, v65
	v_mul_f32_e32 v65, 0xbfb8aa3b, v60
	v_exp_f32_e32 v65, v65
	v_mul_f32_e32 v67, 0xbfb8aa3b, v61
	v_exp_f32_e32 v67, v67
	v_pk_mul_f32 v[62:63], v[62:63], v[68:69] op_sel_hi:[1,0]
	v_add_f32_e32 v65, 1.0, v65
	v_rcp_f32_e32 v72, v65
	v_add_f32_e32 v65, 1.0, v67
	v_mul_f32_e32 v67, 0xbfb8aa3b, v62
	v_pk_mul_f32 v[58:59], v[58:59], v[68:69] op_sel_hi:[1,0]
	v_exp_f32_e32 v67, v67
	v_mul_f32_e32 v69, 0xbfb8aa3b, v63
	v_exp_f32_e32 v69, v69
	v_rcp_f32_e32 v73, v65
	v_add_f32_e32 v65, 1.0, v67
	v_rcp_f32_e32 v74, v65
	v_add_f32_e32 v65, 1.0, v69
	v_rcp_f32_e32 v75, v65
	v_pk_mul_f32 v[56:57], v[56:57], v[68:69] op_sel_hi:[1,0]
	v_pk_mul_f32 v[60:61], v[60:61], v[72:73]
	v_pk_mul_f32 v[52:53], v[52:53], v[68:69] op_sel_hi:[1,0]
	v_pk_mul_f32 v[56:57], v[56:57], v[60:61]
	v_pk_mul_f32 v[60:61], v[62:63], v[74:75]
	v_cvt_pk_bf16_f32 v56, v56, v57
	v_pk_mul_f32 v[58:59], v[58:59], v[60:61]
	v_pk_mul_f32 v[54:55], v[54:55], v[68:69] op_sel_hi:[1,0]
	v_cvt_pk_bf16_f32 v57, v58, v59
	v_mul_f32_e32 v58, 0xbfb8aa3b, v52
	v_mul_f32_e32 v59, 0xbfb8aa3b, v53
	v_exp_f32_e32 v58, v58
	v_exp_f32_e32 v59, v59
	v_mul_f32_e32 v60, 0xbfb8aa3b, v54
	v_mul_f32_e32 v61, 0xbfb8aa3b, v55
	v_exp_f32_e32 v60, v60
	v_exp_f32_e32 v61, v61
	v_add_f32_e32 v58, 1.0, v58
	v_add_f32_e32 v59, 1.0, v59
	v_rcp_f32_e32 v58, v58
	v_rcp_f32_e32 v59, v59
	v_add_f32_e32 v60, 1.0, v60
	v_add_f32_e32 v61, 1.0, v61
	v_rcp_f32_e32 v60, v60
	v_rcp_f32_e32 v61, v61
	v_pk_mul_f32 v[44:45], v[44:45], v[68:69] op_sel_hi:[1,0]
	v_pk_mul_f32 v[52:53], v[52:53], v[58:59]
	v_pk_mul_f32 v[46:47], v[46:47], v[68:69] op_sel_hi:[1,0]
	v_pk_mul_f32 v[44:45], v[44:45], v[52:53]
	v_pk_mul_f32 v[52:53], v[54:55], v[60:61]
	v_cvt_pk_bf16_f32 v58, v44, v45
	v_pk_mul_f32 v[46:47], v[46:47], v[52:53]
	v_mad_i64_i32 v[44:45], s[24:25], v148, s55, v[140:141]
	v_cvt_pk_bf16_f32 v59, v46, v47
	v_lshl_add_u64 v[44:45], v[44:45], 0, v[142:143]
	global_store_dwordx4 v[44:45], v[56:59], off
	v_pk_mul_f32 v[44:45], v[50:51], v[70:71] op_sel_hi:[1,0]
	v_pk_mul_f32 v[46:47], v[48:49], v[70:71] op_sel_hi:[1,0]
	v_mul_f32_e32 v50, 0xbfb8aa3b, v44
	v_mul_f32_e32 v48, 0xbfb8aa3b, v46
	v_mul_f32_e32 v49, 0xbfb8aa3b, v47
	v_mul_f32_e32 v51, 0xbfb8aa3b, v45
	v_exp_f32_e32 v48, v48
	v_exp_f32_e32 v49, v49
	v_exp_f32_e32 v50, v50
	v_exp_f32_e32 v51, v51
	v_add_f32_e32 v48, 1.0, v48
	v_add_f32_e32 v49, 1.0, v49
	v_add_f32_e32 v50, 1.0, v50
	v_add_f32_e32 v51, 1.0, v51
	v_rcp_f32_e32 v48, v48
	v_rcp_f32_e32 v49, v49
	v_rcp_f32_e32 v50, v50
	v_rcp_f32_e32 v51, v51
	v_pk_mul_f32 v[42:43], v[42:43], v[70:71] op_sel_hi:[1,0]
	v_pk_mul_f32 v[40:41], v[40:41], v[70:71] op_sel_hi:[1,0]
	v_pk_mul_f32 v[46:47], v[46:47], v[48:49]
	v_pk_mul_f32 v[44:45], v[44:45], v[50:51]
	v_pk_mul_f32 v[40:41], v[40:41], v[46:47]
	v_pk_mul_f32 v[42:43], v[42:43], v[44:45]
	v_pk_mul_f32 v[36:37], v[36:37], v[70:71] op_sel_hi:[1,0]
	v_cvt_pk_bf16_f32 v40, v40, v41
	v_cvt_pk_bf16_f32 v41, v42, v43
	v_pk_mul_f32 v[38:39], v[38:39], v[70:71] op_sel_hi:[1,0]
	v_mul_f32_e32 v42, 0xbfb8aa3b, v36
	v_mul_f32_e32 v43, 0xbfb8aa3b, v37
	v_exp_f32_e32 v42, v42
	v_exp_f32_e32 v43, v43
	v_mul_f32_e32 v44, 0xbfb8aa3b, v38
	v_mul_f32_e32 v45, 0xbfb8aa3b, v39
	v_exp_f32_e32 v44, v44
	v_exp_f32_e32 v45, v45
	v_add_f32_e32 v42, 1.0, v42
	v_add_f32_e32 v43, 1.0, v43
	v_rcp_f32_e32 v42, v42
	v_rcp_f32_e32 v43, v43
	v_add_f32_e32 v44, 1.0, v44
	v_add_f32_e32 v45, 1.0, v45
	v_rcp_f32_e32 v44, v44
	v_rcp_f32_e32 v45, v45
	v_pk_mul_f32 v[28:29], v[28:29], v[70:71] op_sel_hi:[1,0]
	v_pk_mul_f32 v[36:37], v[36:37], v[42:43]
	v_pk_mul_f32 v[30:31], v[30:31], v[70:71] op_sel_hi:[1,0]
	v_pk_mul_f32 v[28:29], v[28:29], v[36:37]
	v_pk_mul_f32 v[36:37], v[38:39], v[44:45]
	v_cvt_pk_bf16_f32 v42, v28, v29
	v_pk_mul_f32 v[30:31], v[30:31], v[36:37]
	v_mad_i64_i32 v[28:29], s[24:25], v146, s55, v[140:141]
	v_cvt_pk_bf16_f32 v43, v30, v31
; DI u32x2 pk4(f32x4 v) { u32x2 r; r.x = pk2(v[0], v[1]); r.y = pk2(v[2], v[3]); return r; }
; DI float silu_f(float x) { return x * __builtin_amdgcn_rcpf(1.f + __builtin_amdgcn_exp2f(-1.4426950409f * x)); }
; #define PG8_WAIT_V(n) asm volatile("s_waitcnt vmcnt(" #n ")" ::: "memory")
; #define PG8_BAR __builtin_amdgcn_s_barrier()
; #define ROWS8 _Pragma("unroll") for (int ai = 0; ai < 2; ++ai) _Pragma("unroll") for (int m = 0; m < 4; ++m) if (ai == 0 || !hf)
; template <class Epi>
; DI void gemm_phase(LAS unsigned char* lds, int wid, int K, int lda, int ldb, bool bperm, const Sched3& S, const Epi& E) {
;     ...
;     PG8_WAIT_V(0);
;     if (wr == 0) PG8_BAR;
;     DI void operator()(const Acc& acc, const Unit& u, int wr, int wc, int fr, int fq) const {
;     ...
;             ROWS8 { const int r = row0 + ai * HALF + m * 16; const float rs = rsv[ai][m];
;                 u32x4 w;
; #pragma unroll
;                 for (int bj = 0; bj < 2; ++bj) { const f32x4 g = acc[ai][bj][m][0] * rs, uu = acc[ai][bj][m][1] * rs;
;                     f32x4 a; a[0] = silu_f(g[0]) * uu[0]; a[1] = silu_f(g[1]) * uu[1]; a[2] = silu_f(g[2]) * uu[2]; a[3] = silu_f(g[3]) * uu[3];
;                     const u32x2 h = pk4(a); if (bj == 0) { w.x = h.x; w.y = h.y; } else { w.z = h.x; w.w = h.y; } }
;                 *(u32x4*)(WSB(OFF_ACT) + (size_t)r * DFF + ac0) = w;
	v_lshl_add_u64 v[28:29], v[28:29], 0, v[142:143]
	global_store_dwordx4 v[28:29], v[40:43], off
	v_pk_mul_f32 v[28:29], v[34:35], v[66:67] op_sel_hi:[1,0]
	v_pk_mul_f32 v[30:31], v[32:33], v[66:67] op_sel_hi:[1,0]
	v_mul_f32_e32 v34, 0xbfb8aa3b, v28
	v_mul_f32_e32 v32, 0xbfb8aa3b, v30
	v_mul_f32_e32 v33, 0xbfb8aa3b, v31
	v_mul_f32_e32 v35, 0xbfb8aa3b, v29
	v_exp_f32_e32 v32, v32
	v_exp_f32_e32 v33, v33
	v_exp_f32_e32 v34, v34
	v_exp_f32_e32 v35, v35
	v_add_f32_e32 v32, 1.0, v32
	v_add_f32_e32 v33, 1.0, v33
	v_add_f32_e32 v34, 1.0, v34
	v_add_f32_e32 v35, 1.0, v35
	v_rcp_f32_e32 v32, v32
	v_rcp_f32_e32 v33, v33
	v_rcp_f32_e32 v34, v34
	v_rcp_f32_e32 v35, v35
	v_pk_mul_f32 v[26:27], v[26:27], v[66:67] op_sel_hi:[1,0]
	v_pk_mul_f32 v[24:25], v[24:25], v[66:67] op_sel_hi:[1,0]
	v_pk_mul_f32 v[30:31], v[30:31], v[32:33]
	v_pk_mul_f32 v[28:29], v[28:29], v[34:35]
	v_pk_mul_f32 v[24:25], v[24:25], v[30:31]
	v_pk_mul_f32 v[26:27], v[26:27], v[28:29]
	v_pk_mul_f32 v[20:21], v[20:21], v[66:67] op_sel_hi:[1,0]
	v_cvt_pk_bf16_f32 v24, v24, v25
	v_cvt_pk_bf16_f32 v25, v26, v27
	v_pk_mul_f32 v[22:23], v[22:23], v[66:67] op_sel_hi:[1,0]
	v_mul_f32_e32 v26, 0xbfb8aa3b, v20
	v_mul_f32_e32 v27, 0xbfb8aa3b, v21
	v_exp_f32_e32 v26, v26
	v_exp_f32_e32 v27, v27
	v_mul_f32_e32 v28, 0xbfb8aa3b, v22
	v_mul_f32_e32 v29, 0xbfb8aa3b, v23
	v_exp_f32_e32 v28, v28
	v_exp_f32_e32 v29, v29
	v_add_f32_e32 v26, 1.0, v26
	v_add_f32_e32 v27, 1.0, v27
	v_rcp_f32_e32 v26, v26
	v_rcp_f32_e32 v27, v27
	v_add_f32_e32 v28, 1.0, v28
	v_add_f32_e32 v29, 1.0, v29
	v_rcp_f32_e32 v28, v28
	v_rcp_f32_e32 v29, v29
	v_fmamk_f32 v64, v149, 0x3a000000, v163
	v_rsq_f32_e32 v64, v64
	v_pk_mul_f32 v[12:13], v[12:13], v[66:67] op_sel_hi:[1,0]
	v_pk_mul_f32 v[20:21], v[20:21], v[26:27]
	v_pk_mul_f32 v[14:15], v[14:15], v[66:67] op_sel_hi:[1,0]
	v_pk_mul_f32 v[12:13], v[12:13], v[20:21]
	v_pk_mul_f32 v[20:21], v[22:23], v[28:29]
	v_cvt_pk_bf16_f32 v26, v12, v13
	v_pk_mul_f32 v[14:15], v[14:15], v[20:21]
	v_mad_i64_i32 v[12:13], s[24:25], v144, s55, v[140:141]
	v_cvt_pk_bf16_f32 v27, v14, v15
	v_lshl_add_u64 v[12:13], v[12:13], 0, v[142:143]
	global_store_dwordx4 v[12:13], v[24:27], off
	v_pk_mul_f32 v[12:13], v[18:19], v[64:65] op_sel_hi:[1,0]
	v_pk_mul_f32 v[14:15], v[16:17], v[64:65] op_sel_hi:[1,0]
	v_mul_f32_e32 v18, 0xbfb8aa3b, v12
	v_mul_f32_e32 v16, 0xbfb8aa3b, v14
	v_mul_f32_e32 v17, 0xbfb8aa3b, v15
	v_mul_f32_e32 v19, 0xbfb8aa3b, v13
	v_exp_f32_e32 v16, v16
	v_exp_f32_e32 v17, v17
	v_exp_f32_e32 v18, v18
	v_exp_f32_e32 v19, v19
	v_add_f32_e32 v16, 1.0, v16
	v_add_f32_e32 v17, 1.0, v17
	v_add_f32_e32 v18, 1.0, v18
	v_add_f32_e32 v19, 1.0, v19
	v_rcp_f32_e32 v16, v16
	v_rcp_f32_e32 v17, v17
	v_rcp_f32_e32 v18, v18
	v_rcp_f32_e32 v19, v19
	v_pk_mul_f32 v[10:11], v[10:11], v[64:65] op_sel_hi:[1,0]
	v_pk_mul_f32 v[8:9], v[8:9], v[64:65] op_sel_hi:[1,0]
	v_pk_mul_f32 v[14:15], v[14:15], v[16:17]
	v_pk_mul_f32 v[12:13], v[12:13], v[18:19]
	v_pk_mul_f32 v[8:9], v[8:9], v[14:15]
	v_pk_mul_f32 v[10:11], v[10:11], v[12:13]
	v_pk_mul_f32 v[4:5], v[4:5], v[64:65] op_sel_hi:[1,0]
	v_cvt_pk_bf16_f32 v8, v8, v9
	v_cvt_pk_bf16_f32 v9, v10, v11
	v_pk_mul_f32 v[6:7], v[6:7], v[64:65] op_sel_hi:[1,0]
	v_mul_f32_e32 v10, 0xbfb8aa3b, v4
	v_mul_f32_e32 v11, 0xbfb8aa3b, v5
	v_exp_f32_e32 v10, v10
	v_exp_f32_e32 v11, v11
	v_mul_f32_e32 v12, 0xbfb8aa3b, v6
	v_mul_f32_e32 v13, 0xbfb8aa3b, v7
	v_exp_f32_e32 v12, v12
	v_exp_f32_e32 v13, v13
	v_add_f32_e32 v10, 1.0, v10
	v_add_f32_e32 v11, 1.0, v11
	v_rcp_f32_e32 v10, v10
	v_rcp_f32_e32 v11, v11
	v_add_f32_e32 v12, 1.0, v12
	v_add_f32_e32 v13, 1.0, v13
	v_rcp_f32_e32 v12, v12
	v_rcp_f32_e32 v13, v13
	v_pk_mul_f32 v[0:1], v[0:1], v[64:65] op_sel_hi:[1,0]
	v_pk_mul_f32 v[4:5], v[4:5], v[10:11]
	v_pk_mul_f32 v[2:3], v[2:3], v[64:65] op_sel_hi:[1,0]
	v_pk_mul_f32 v[0:1], v[0:1], v[4:5]
	v_pk_mul_f32 v[4:5], v[6:7], v[12:13]
	v_cvt_pk_bf16_f32 v10, v0, v1
	v_pk_mul_f32 v[2:3], v[2:3], v[4:5]
	v_mad_i64_i32 v[0:1], s[24:25], v138, s55, v[140:141]
	v_cvt_pk_bf16_f32 v11, v2, v3
	v_lshl_add_u64 v[0:1], v[0:1], 0, v[142:143]
	global_store_dwordx4 v[0:1], v[8:11], off
	s_cbranch_vccz .LBB0_702
	s_waitcnt vmcnt(0)
	s_cmpk_gt_u32 s88, 0xff
	s_cbranch_scc1 .LBB0_709
	s_barrier
